# v048 + LRU pass-3 chunk-aggregate staging: 16 masked loads in flight, single wait
# speedup vs baseline: 1.0240x; 1.0097x over previous
.LBB0_296:
	s_mul_i32 s2, s28, s70
	s_add_i32 s2, s2, s27
	s_bfe_u32 s37, s2, 0x60003
	s_mov_b64 s[8:9], s[74:75]
	s_waitcnt lgkmcnt(0)
	s_barrier
	s_lshl_b32 s35, s37, 6
	v_lshlrev_b32_e32 v144, 1, v151
	s_add_i32 s3, s35, -2
	v_lshl_add_u64 v[8:9], s[8:9], 0, v[144:145]
	s_mov_b64 s[8:9], 0x91e0000
	s_ashr_i32 s2, s2, 9
	v_lshl_add_u64 v[48:49], v[8:9], 0, s[8:9]
	v_add_u32_e32 v50, s3, v154
	s_waitcnt vmcnt(0)
	v_mov_b64_e32 v[14:15], v[6:7]
	s_lshl_b32 s36, s2, 12
	v_cmp_gt_u32_e64 s[8:9], s67, v50
	v_mov_b64_e32 v[12:13], v[4:5]
	v_mov_b64_e32 v[10:11], v[2:3]
	v_mov_b64_e32 v[8:9], v[0:1]
	v_mov_b64_e32 v[216:217], 0
	v_mov_b64_e32 v[218:219], 0
	s_and_saveexec_b64 s[12:13], s[8:9]
	v_or_b32_e32 v232, s36, v50
	v_ashrrev_i32_e32 v233, 31, v232
	v_lshlrev_b64 v[232:233], 10, v[232:233]
	v_lshl_add_u64 v[232:233], v[48:49], 0, v[232:233]
	global_load_dwordx4 v[216:219], v[232:233], off
	s_or_b64 exec, exec, s[12:13]
	v_add_u32_e32 v51, 1, v50
	v_cmp_gt_u32_e64 s[8:9], s67, v51
	v_mov_b64_e32 v[220:221], 0
	v_mov_b64_e32 v[222:223], 0
	s_and_saveexec_b64 s[12:13], s[8:9]
	v_or_b32_e32 v234, s36, v51
	v_ashrrev_i32_e32 v235, 31, v234
	v_lshlrev_b64 v[234:235], 10, v[234:235]
	v_lshl_add_u64 v[234:235], v[48:49], 0, v[234:235]
	global_load_dwordx4 v[220:223], v[234:235], off
	s_or_b64 exec, exec, s[12:13]
	v_add_u32_e32 v51, s35, v154
	v_cmp_gt_u32_e64 s[8:9], s67, v51
	v_mov_b64_e32 v[224:225], 0
	v_mov_b64_e32 v[226:227], 0
	s_and_saveexec_b64 s[12:13], s[8:9]
	v_or_b32_e32 v236, s36, v51
	v_ashrrev_i32_e32 v237, 31, v236
	v_lshlrev_b64 v[236:237], 10, v[236:237]
	v_lshl_add_u64 v[236:237], v[48:49], 0, v[236:237]
	global_load_dwordx4 v[224:227], v[236:237], off
	s_or_b64 exec, exec, s[12:13]
	v_add_u32_e32 v50, 3, v50
	v_cmp_gt_u32_e64 s[8:9], s67, v50
	v_mov_b64_e32 v[228:229], 0
	v_mov_b64_e32 v[230:231], 0
	s_and_saveexec_b64 s[12:13], s[8:9]
	v_or_b32_e32 v238, s36, v50
	v_ashrrev_i32_e32 v239, 31, v238
	v_lshlrev_b64 v[238:239], 10, v[238:239]
	v_lshl_add_u64 v[238:239], v[48:49], 0, v[238:239]
	global_load_dwordx4 v[228:231], v[238:239], off
	s_or_b64 exec, exec, s[12:13]
	s_waitcnt vmcnt(0)
	v_lshlrev_b32_e32 v52, 16, v216
	v_and_b32_e32 v53, 0xffff0000, v216
	v_lshlrev_b32_e32 v8, 16, v217
	v_and_b32_e32 v9, 0xffff0000, v217
	v_lshlrev_b32_e32 v12, 16, v218
	v_and_b32_e32 v13, 0xffff0000, v218
	v_lshlrev_b32_e32 v10, 16, v219
	v_and_b32_e32 v11, 0xffff0000, v219
	v_pk_fma_f32 v[14:15], v[22:23], v[10:11], v[6:7]
	v_pk_fma_f32 v[12:13], v[20:21], v[12:13], v[4:5]
	v_pk_fma_f32 v[10:11], v[18:19], v[8:9], v[2:3]
	v_pk_fma_f32 v[8:9], v[16:17], v[52:53], v[0:1]
	v_lshlrev_b32_e32 v56, 16, v220
	v_and_b32_e32 v57, 0xffff0000, v220
	v_lshlrev_b32_e32 v52, 16, v221
	v_and_b32_e32 v53, 0xffff0000, v221
	v_lshlrev_b32_e32 v58, 16, v222
	v_and_b32_e32 v59, 0xffff0000, v222
	v_lshlrev_b32_e32 v54, 16, v223
	v_and_b32_e32 v55, 0xffff0000, v223
	v_pk_fma_f32 v[14:15], v[30:31], v[54:55], v[14:15]
	v_pk_fma_f32 v[12:13], v[28:29], v[58:59], v[12:13]
	v_pk_fma_f32 v[10:11], v[26:27], v[52:53], v[10:11]
	v_pk_fma_f32 v[8:9], v[24:25], v[56:57], v[8:9]
	v_lshlrev_b32_e32 v56, 16, v224
	v_and_b32_e32 v57, 0xffff0000, v224
	v_lshlrev_b32_e32 v52, 16, v225
	v_and_b32_e32 v53, 0xffff0000, v225
	v_lshlrev_b32_e32 v58, 16, v226
	v_and_b32_e32 v59, 0xffff0000, v226
	v_lshlrev_b32_e32 v54, 16, v227
	v_and_b32_e32 v55, 0xffff0000, v227
	v_pk_fma_f32 v[14:15], v[38:39], v[54:55], v[14:15]
	v_pk_fma_f32 v[12:13], v[36:37], v[58:59], v[12:13]
	v_pk_fma_f32 v[10:11], v[34:35], v[52:53], v[10:11]
	v_pk_fma_f32 v[8:9], v[32:33], v[56:57], v[8:9]
	v_lshlrev_b32_e32 v54, 16, v228
	v_and_b32_e32 v55, 0xffff0000, v228
	v_lshlrev_b32_e32 v50, 16, v229
	v_and_b32_e32 v51, 0xffff0000, v229
	v_lshlrev_b32_e32 v56, 16, v230
	v_and_b32_e32 v57, 0xffff0000, v230
	v_lshlrev_b32_e32 v52, 16, v231
	v_and_b32_e32 v53, 0xffff0000, v231
	v_pk_fma_f32 v[14:15], v[46:47], v[52:53], v[14:15]
	v_pk_fma_f32 v[12:13], v[44:45], v[56:57], v[12:13]
	v_pk_fma_f32 v[10:11], v[42:43], v[50:51], v[10:11]
	v_pk_fma_f32 v[8:9], v[40:41], v[54:55], v[8:9]
	v_cvt_pk_bf16_f32 v8, v8, v9
	v_cvt_pk_bf16_f32 v9, v10, v11
	v_cvt_pk_bf16_f32 v10, v12, v13
	v_cvt_pk_bf16_f32 v11, v14, v15
	ds_write_b128 v159, v[8:11]
	v_add_u32_e32 v50, s3, v157
	v_mov_b64_e32 v[14:15], v[6:7]
	v_cmp_gt_u32_e64 s[8:9], s67, v50
	v_mov_b64_e32 v[12:13], v[4:5]
	v_mov_b64_e32 v[10:11], v[2:3]
	v_mov_b64_e32 v[8:9], v[0:1]
	v_mov_b64_e32 v[216:217], 0
	v_mov_b64_e32 v[218:219], 0
	s_and_saveexec_b64 s[12:13], s[8:9]
	v_or_b32_e32 v232, s36, v50
	v_ashrrev_i32_e32 v233, 31, v232
	v_lshlrev_b64 v[232:233], 10, v[232:233]
	v_lshl_add_u64 v[232:233], v[48:49], 0, v[232:233]
	global_load_dwordx4 v[216:219], v[232:233], off
	s_or_b64 exec, exec, s[12:13]
	v_add_u32_e32 v51, 1, v50
	v_cmp_gt_u32_e64 s[8:9], s67, v51
	v_mov_b64_e32 v[220:221], 0
	v_mov_b64_e32 v[222:223], 0
	s_and_saveexec_b64 s[12:13], s[8:9]
	v_or_b32_e32 v234, s36, v51
	v_ashrrev_i32_e32 v235, 31, v234
	v_lshlrev_b64 v[234:235], 10, v[234:235]
	v_lshl_add_u64 v[234:235], v[48:49], 0, v[234:235]
	global_load_dwordx4 v[220:223], v[234:235], off
	s_or_b64 exec, exec, s[12:13]
	v_add_u32_e32 v51, s35, v157
	v_cmp_gt_u32_e64 s[8:9], s67, v51
	v_mov_b64_e32 v[224:225], 0
	v_mov_b64_e32 v[226:227], 0
	s_and_saveexec_b64 s[12:13], s[8:9]
	v_or_b32_e32 v236, s36, v51
	v_ashrrev_i32_e32 v237, 31, v236
	v_lshlrev_b64 v[236:237], 10, v[236:237]
	v_lshl_add_u64 v[236:237], v[48:49], 0, v[236:237]
	global_load_dwordx4 v[224:227], v[236:237], off
	s_or_b64 exec, exec, s[12:13]
	v_add_u32_e32 v50, 3, v50
	v_cmp_gt_u32_e64 s[8:9], s67, v50
	v_mov_b64_e32 v[228:229], 0
	v_mov_b64_e32 v[230:231], 0
	s_and_saveexec_b64 s[12:13], s[8:9]
	v_or_b32_e32 v238, s36, v50
	v_ashrrev_i32_e32 v239, 31, v238
	v_lshlrev_b64 v[238:239], 10, v[238:239]
	v_lshl_add_u64 v[238:239], v[48:49], 0, v[238:239]
	global_load_dwordx4 v[228:231], v[238:239], off
	s_or_b64 exec, exec, s[12:13]
	s_waitcnt vmcnt(0)
	v_lshlrev_b32_e32 v52, 16, v216
	v_and_b32_e32 v53, 0xffff0000, v216
	v_lshlrev_b32_e32 v8, 16, v217
	v_and_b32_e32 v9, 0xffff0000, v217
	v_lshlrev_b32_e32 v12, 16, v218
	v_and_b32_e32 v13, 0xffff0000, v218
	v_lshlrev_b32_e32 v10, 16, v219
	v_and_b32_e32 v11, 0xffff0000, v219
	v_pk_fma_f32 v[14:15], v[22:23], v[10:11], v[6:7]
	v_pk_fma_f32 v[12:13], v[20:21], v[12:13], v[4:5]
	v_pk_fma_f32 v[10:11], v[18:19], v[8:9], v[2:3]
	v_pk_fma_f32 v[8:9], v[16:17], v[52:53], v[0:1]
	v_lshlrev_b32_e32 v56, 16, v220
	v_and_b32_e32 v57, 0xffff0000, v220
	v_lshlrev_b32_e32 v52, 16, v221
	v_and_b32_e32 v53, 0xffff0000, v221
	v_lshlrev_b32_e32 v58, 16, v222
	v_and_b32_e32 v59, 0xffff0000, v222
	v_lshlrev_b32_e32 v54, 16, v223
	v_and_b32_e32 v55, 0xffff0000, v223
	v_pk_fma_f32 v[14:15], v[30:31], v[54:55], v[14:15]
	v_pk_fma_f32 v[12:13], v[28:29], v[58:59], v[12:13]
	v_pk_fma_f32 v[10:11], v[26:27], v[52:53], v[10:11]
	v_pk_fma_f32 v[8:9], v[24:25], v[56:57], v[8:9]
	v_lshlrev_b32_e32 v56, 16, v224
	v_and_b32_e32 v57, 0xffff0000, v224
	v_lshlrev_b32_e32 v52, 16, v225
	v_and_b32_e32 v53, 0xffff0000, v225
	v_lshlrev_b32_e32 v58, 16, v226
	v_and_b32_e32 v59, 0xffff0000, v226
	v_lshlrev_b32_e32 v54, 16, v227
	v_and_b32_e32 v55, 0xffff0000, v227
	v_pk_fma_f32 v[14:15], v[38:39], v[54:55], v[14:15]
	v_pk_fma_f32 v[12:13], v[36:37], v[58:59], v[12:13]
	v_pk_fma_f32 v[10:11], v[34:35], v[52:53], v[10:11]
	v_pk_fma_f32 v[8:9], v[32:33], v[56:57], v[8:9]
	v_lshlrev_b32_e32 v52, 16, v228
	v_and_b32_e32 v53, 0xffff0000, v228
	v_lshlrev_b32_e32 v48, 16, v229
	v_and_b32_e32 v49, 0xffff0000, v229
	v_lshlrev_b32_e32 v54, 16, v230
	v_and_b32_e32 v55, 0xffff0000, v230
	v_lshlrev_b32_e32 v50, 16, v231
	v_and_b32_e32 v51, 0xffff0000, v231
	v_pk_fma_f32 v[14:15], v[46:47], v[50:51], v[14:15]
	v_pk_fma_f32 v[12:13], v[44:45], v[54:55], v[12:13]
	v_pk_fma_f32 v[10:11], v[42:43], v[48:49], v[10:11]
	v_pk_fma_f32 v[8:9], v[40:41], v[52:53], v[8:9]
	s_mov_b64 s[8:9], s[74:75]
	v_cvt_pk_bf16_f32 v8, v8, v9
	v_cvt_pk_bf16_f32 v9, v10, v11
	v_cvt_pk_bf16_f32 v10, v12, v13
	v_cvt_pk_bf16_f32 v11, v14, v15
	ds_write_b128 v160, v[8:11]
	s_lshl_b32 s3, s26, 3
	s_add_u32 s8, s8, s3
	s_addc_u32 s9, s9, 0
	v_mov_b32_e32 v141, v145
	v_lshl_add_u64 v[8:9], s[8:9], 0, v[140:141]
	s_mov_b64 s[8:9], 0x115e0000
	v_lshl_add_u64 v[8:9], v[8:9], 0, s[8:9]
	s_lshl_b32 s12, s2, 1
	v_add_u32_e32 v12, v156, v155
	v_cmp_ne_u32_e64 s[8:9], s37, v76
	s_and_saveexec_b64 s[2:3], s[8:9]
	v_cmp_le_i32_e64 s[8:9], s37, v76
	s_nop 1
	v_cndmask_b32_e64 v10, 0, 1, s[8:9]
	v_or_b32_e32 v10, s12, v10
	v_ashrrev_i32_e32 v11, 31, v10
	v_lshlrev_b64 v[10:11], 18, v[10:11]
	v_lshl_add_u64 v[10:11], v[8:9], 0, v[10:11]
	v_lshl_add_u64 v[10:11], v[10:11], 0, v[78:79]
	global_load_dwordx2 v[216:217], v[10:11], off
	s_or_b64 exec, exec, s[2:3]
	v_cmp_ne_u32_e64 s[8:9], s37, v84
	s_and_saveexec_b64 s[2:3], s[8:9]
	v_cmp_le_i32_e64 s[8:9], s37, v84
	s_nop 1
	v_cndmask_b32_e64 v10, 0, 1, s[8:9]
	v_or_b32_e32 v10, s12, v10
	v_ashrrev_i32_e32 v11, 31, v10
	v_lshlrev_b64 v[10:11], 18, v[10:11]
	v_lshl_add_u64 v[10:11], v[8:9], 0, v[10:11]
	v_lshl_add_u64 v[10:11], v[10:11], 0, v[86:87]
	global_load_dwordx2 v[218:219], v[10:11], off
	s_or_b64 exec, exec, s[2:3]
	v_cmp_ne_u32_e64 s[8:9], s37, v92
	s_and_saveexec_b64 s[2:3], s[8:9]
	v_cmp_le_i32_e64 s[8:9], s37, v92
	s_nop 1
	v_cndmask_b32_e64 v10, 0, 1, s[8:9]
	v_or_b32_e32 v10, s12, v10
	v_ashrrev_i32_e32 v11, 31, v10
	v_lshlrev_b64 v[10:11], 18, v[10:11]
	v_lshl_add_u64 v[10:11], v[8:9], 0, v[10:11]
	v_lshl_add_u64 v[10:11], v[10:11], 0, v[94:95]
	global_load_dwordx2 v[220:221], v[10:11], off
	s_or_b64 exec, exec, s[2:3]
	v_cmp_ne_u32_e64 s[8:9], s37, v100
	s_and_saveexec_b64 s[2:3], s[8:9]
	v_cmp_le_i32_e64 s[8:9], s37, v100
	s_nop 1
	v_cndmask_b32_e64 v10, 0, 1, s[8:9]
	v_or_b32_e32 v10, s12, v10
	v_ashrrev_i32_e32 v11, 31, v10
	v_lshlrev_b64 v[10:11], 18, v[10:11]
	v_lshl_add_u64 v[10:11], v[8:9], 0, v[10:11]
	v_lshl_add_u64 v[10:11], v[10:11], 0, v[102:103]
	global_load_dwordx2 v[222:223], v[10:11], off
	s_or_b64 exec, exec, s[2:3]
	v_cmp_ne_u32_e64 s[8:9], s37, v108
	s_and_saveexec_b64 s[2:3], s[8:9]
	v_cmp_le_i32_e64 s[8:9], s37, v108
	s_nop 1
	v_cndmask_b32_e64 v10, 0, 1, s[8:9]
	v_or_b32_e32 v10, s12, v10
	v_ashrrev_i32_e32 v11, 31, v10
	v_lshlrev_b64 v[10:11], 18, v[10:11]
	v_lshl_add_u64 v[10:11], v[8:9], 0, v[10:11]
	v_lshl_add_u64 v[10:11], v[10:11], 0, v[110:111]
	global_load_dwordx2 v[224:225], v[10:11], off
	s_or_b64 exec, exec, s[2:3]
	v_cmp_ne_u32_e64 s[8:9], s37, v116
	s_and_saveexec_b64 s[2:3], s[8:9]
	v_cmp_le_i32_e64 s[8:9], s37, v116
	s_nop 1
	v_cndmask_b32_e64 v10, 0, 1, s[8:9]
	v_or_b32_e32 v10, s12, v10
	v_ashrrev_i32_e32 v11, 31, v10
	v_lshlrev_b64 v[10:11], 18, v[10:11]
	v_lshl_add_u64 v[10:11], v[8:9], 0, v[10:11]
	v_lshl_add_u64 v[10:11], v[10:11], 0, v[118:119]
	global_load_dwordx2 v[226:227], v[10:11], off
	s_or_b64 exec, exec, s[2:3]
	v_cmp_ne_u32_e64 s[8:9], s37, v124
	s_and_saveexec_b64 s[2:3], s[8:9]
	v_cmp_le_i32_e64 s[8:9], s37, v124
	s_nop 1
	v_cndmask_b32_e64 v10, 0, 1, s[8:9]
	v_or_b32_e32 v10, s12, v10
	v_ashrrev_i32_e32 v11, 31, v10
	v_lshlrev_b64 v[10:11], 18, v[10:11]
	v_lshl_add_u64 v[10:11], v[8:9], 0, v[10:11]
	v_lshl_add_u64 v[10:11], v[10:11], 0, v[126:127]
	global_load_dwordx2 v[228:229], v[10:11], off
	s_or_b64 exec, exec, s[2:3]
	v_cmp_ne_u32_e64 s[8:9], s37, v132
	s_and_saveexec_b64 s[2:3], s[8:9]
	v_cmp_le_i32_e64 s[8:9], s37, v132
	s_nop 1
	v_cndmask_b32_e64 v10, 0, 1, s[8:9]
	v_or_b32_e32 v10, s12, v10
	v_ashrrev_i32_e32 v11, 31, v10
	v_lshlrev_b64 v[10:11], 18, v[10:11]
	v_lshl_add_u64 v[10:11], v[8:9], 0, v[10:11]
	v_lshl_add_u64 v[10:11], v[10:11], 0, v[134:135]
	global_load_dwordx2 v[230:231], v[10:11], off
	s_or_b64 exec, exec, s[2:3]
	v_cmp_ne_u32_e64 s[8:9], s37, v80
	s_and_saveexec_b64 s[2:3], s[8:9]
	v_cmp_le_i32_e64 s[8:9], s37, v80
	s_nop 1
	v_cndmask_b32_e64 v10, 0, 1, s[8:9]
	v_or_b32_e32 v10, s12, v10
	v_ashrrev_i32_e32 v11, 31, v10
	v_lshlrev_b64 v[10:11], 18, v[10:11]
	v_lshl_add_u64 v[10:11], v[8:9], 0, v[10:11]
	v_lshl_add_u64 v[10:11], v[10:11], 0, v[82:83]
	global_load_dwordx2 v[232:233], v[10:11], off
	s_or_b64 exec, exec, s[2:3]
	v_cmp_ne_u32_e64 s[8:9], s37, v88
	s_and_saveexec_b64 s[2:3], s[8:9]
	v_cmp_le_i32_e64 s[8:9], s37, v88
	s_nop 1
	v_cndmask_b32_e64 v10, 0, 1, s[8:9]
	v_or_b32_e32 v10, s12, v10
	v_ashrrev_i32_e32 v11, 31, v10
	v_lshlrev_b64 v[10:11], 18, v[10:11]
	v_lshl_add_u64 v[10:11], v[8:9], 0, v[10:11]
	v_lshl_add_u64 v[10:11], v[10:11], 0, v[90:91]
	global_load_dwordx2 v[234:235], v[10:11], off
	s_or_b64 exec, exec, s[2:3]
	v_cmp_ne_u32_e64 s[8:9], s37, v96
	s_and_saveexec_b64 s[2:3], s[8:9]
	v_cmp_le_i32_e64 s[8:9], s37, v96
	s_nop 1
	v_cndmask_b32_e64 v10, 0, 1, s[8:9]
	v_or_b32_e32 v10, s12, v10
	v_ashrrev_i32_e32 v11, 31, v10
	v_lshlrev_b64 v[10:11], 18, v[10:11]
	v_lshl_add_u64 v[10:11], v[8:9], 0, v[10:11]
	v_lshl_add_u64 v[10:11], v[10:11], 0, v[98:99]
	global_load_dwordx2 v[236:237], v[10:11], off
	s_or_b64 exec, exec, s[2:3]
	v_cmp_ne_u32_e64 s[8:9], s37, v104
	s_and_saveexec_b64 s[2:3], s[8:9]
	v_cmp_le_i32_e64 s[8:9], s37, v104
	s_nop 1
	v_cndmask_b32_e64 v10, 0, 1, s[8:9]
	v_or_b32_e32 v10, s12, v10
	v_ashrrev_i32_e32 v11, 31, v10
	v_lshlrev_b64 v[10:11], 18, v[10:11]
	v_lshl_add_u64 v[10:11], v[8:9], 0, v[10:11]
	v_lshl_add_u64 v[10:11], v[10:11], 0, v[106:107]
	global_load_dwordx2 v[238:239], v[10:11], off
	s_or_b64 exec, exec, s[2:3]
	v_cmp_ne_u32_e64 s[8:9], s37, v112
	s_and_saveexec_b64 s[2:3], s[8:9]
	v_cmp_le_i32_e64 s[8:9], s37, v112
	s_nop 1
	v_cndmask_b32_e64 v10, 0, 1, s[8:9]
	v_or_b32_e32 v10, s12, v10
	v_ashrrev_i32_e32 v11, 31, v10
	v_lshlrev_b64 v[10:11], 18, v[10:11]
	v_lshl_add_u64 v[10:11], v[8:9], 0, v[10:11]
	v_lshl_add_u64 v[10:11], v[10:11], 0, v[114:115]
	global_load_dwordx2 v[240:241], v[10:11], off
	s_or_b64 exec, exec, s[2:3]
	v_cmp_ne_u32_e64 s[8:9], s37, v120
	s_and_saveexec_b64 s[2:3], s[8:9]
	v_cmp_le_i32_e64 s[8:9], s37, v120
	s_nop 1
	v_cndmask_b32_e64 v10, 0, 1, s[8:9]
	v_or_b32_e32 v10, s12, v10
	v_ashrrev_i32_e32 v11, 31, v10
	v_lshlrev_b64 v[10:11], 18, v[10:11]
	v_lshl_add_u64 v[10:11], v[8:9], 0, v[10:11]
	v_lshl_add_u64 v[10:11], v[10:11], 0, v[122:123]
	global_load_dwordx2 v[242:243], v[10:11], off
	s_or_b64 exec, exec, s[2:3]
	v_cmp_ne_u32_e64 s[8:9], s37, v128
	s_and_saveexec_b64 s[2:3], s[8:9]
	v_cmp_le_i32_e64 s[8:9], s37, v128
	s_nop 1
	v_cndmask_b32_e64 v10, 0, 1, s[8:9]
	v_or_b32_e32 v10, s12, v10
	v_ashrrev_i32_e32 v11, 31, v10
	v_lshlrev_b64 v[10:11], 18, v[10:11]
	v_lshl_add_u64 v[10:11], v[8:9], 0, v[10:11]
	v_lshl_add_u64 v[10:11], v[10:11], 0, v[130:131]
	global_load_dwordx2 v[244:245], v[10:11], off
	s_or_b64 exec, exec, s[2:3]
	v_cmp_ne_u32_e64 s[8:9], s37, v136
	s_and_saveexec_b64 s[2:3], s[8:9]
	v_cmp_le_i32_e64 s[8:9], s37, v136
	s_nop 1
	v_cndmask_b32_e64 v10, 0, 1, s[8:9]
	v_or_b32_e32 v10, s12, v10
	v_ashrrev_i32_e32 v11, 31, v10
	v_lshlrev_b64 v[10:11], 18, v[10:11]
	v_lshl_add_u64 v[10:11], v[8:9], 0, v[10:11]
	v_lshl_add_u64 v[10:11], v[10:11], 0, v[138:139]
	global_load_dwordx2 v[246:247], v[10:11], off
	s_or_b64 exec, exec, s[2:3]
	s_waitcnt vmcnt(0)
	v_cmp_ne_u32_e64 s[8:9], s37, v76
	s_and_saveexec_b64 s[2:3], s[8:9]
	ds_write_b64 v12, v[216:217] offset:8192
	s_or_b64 exec, exec, s[2:3]
	v_cmp_ne_u32_e64 s[8:9], s37, v84
	s_and_saveexec_b64 s[2:3], s[8:9]
	ds_write_b64 v81, v[218:219] offset:8192
	s_or_b64 exec, exec, s[2:3]
	v_cmp_ne_u32_e64 s[8:9], s37, v92
	s_and_saveexec_b64 s[2:3], s[8:9]
	ds_write_b64 v89, v[220:221] offset:8192
	s_or_b64 exec, exec, s[2:3]
	v_cmp_ne_u32_e64 s[8:9], s37, v100
	s_and_saveexec_b64 s[2:3], s[8:9]
	ds_write_b64 v97, v[222:223] offset:8192
	s_or_b64 exec, exec, s[2:3]
	v_cmp_ne_u32_e64 s[8:9], s37, v108
	s_and_saveexec_b64 s[2:3], s[8:9]
	ds_write_b64 v105, v[224:225] offset:8192
	s_or_b64 exec, exec, s[2:3]
	v_cmp_ne_u32_e64 s[8:9], s37, v116
	s_and_saveexec_b64 s[2:3], s[8:9]
	ds_write_b64 v113, v[226:227] offset:8192
	s_or_b64 exec, exec, s[2:3]
	v_cmp_ne_u32_e64 s[8:9], s37, v124
	s_and_saveexec_b64 s[2:3], s[8:9]
	ds_write_b64 v121, v[228:229] offset:8192
	s_or_b64 exec, exec, s[2:3]
	v_cmp_ne_u32_e64 s[8:9], s37, v132
	s_and_saveexec_b64 s[2:3], s[8:9]
	ds_write_b64 v129, v[230:231] offset:8192
	s_or_b64 exec, exec, s[2:3]
	v_cmp_ne_u32_e64 s[8:9], s37, v80
	s_and_saveexec_b64 s[2:3], s[8:9]
	ds_write_b64 v77, v[232:233] offset:8192
	s_or_b64 exec, exec, s[2:3]
	v_cmp_ne_u32_e64 s[8:9], s37, v88
	s_and_saveexec_b64 s[2:3], s[8:9]
	ds_write_b64 v85, v[234:235] offset:8192
	s_or_b64 exec, exec, s[2:3]
	v_cmp_ne_u32_e64 s[8:9], s37, v96
	s_and_saveexec_b64 s[2:3], s[8:9]
	ds_write_b64 v93, v[236:237] offset:8192
	s_or_b64 exec, exec, s[2:3]
	v_cmp_ne_u32_e64 s[8:9], s37, v104
	s_and_saveexec_b64 s[2:3], s[8:9]
	ds_write_b64 v101, v[238:239] offset:8192
	s_or_b64 exec, exec, s[2:3]
	v_cmp_ne_u32_e64 s[8:9], s37, v112
	s_and_saveexec_b64 s[2:3], s[8:9]
	ds_write_b64 v109, v[240:241] offset:8192
	s_or_b64 exec, exec, s[2:3]
	v_cmp_ne_u32_e64 s[8:9], s37, v120
	s_and_saveexec_b64 s[2:3], s[8:9]
	ds_write_b64 v117, v[242:243] offset:8192
	s_or_b64 exec, exec, s[2:3]
	v_cmp_ne_u32_e64 s[8:9], s37, v128
	s_and_saveexec_b64 s[2:3], s[8:9]
	ds_write_b64 v125, v[244:245] offset:8192
	s_or_b64 exec, exec, s[2:3]
	v_cmp_ne_u32_e64 s[8:9], s37, v136
	s_and_saveexec_b64 s[2:3], s[8:9]
	ds_write_b64 v133, v[246:247] offset:8192
	s_or_b64 exec, exec, s[2:3]
